# P0 in-projection weight transpose (masked-column variant): the 8 dword loads of each loop trip issued together and waited once instead of one load and one vmcnt(0) per element
# speedup vs baseline: 1.0073x; 1.0073x over previous
.LBB0_40:
.LBB0_41:
	v_mov_b32_e32 v100, 0
	v_mov_b32_e32 v101, 0
	v_mov_b32_e32 v102, 0
	v_mov_b32_e32 v103, 0
	v_mov_b32_e32 v104, 0
	v_mov_b32_e32 v105, 0
	v_mov_b32_e32 v106, 0
	v_mov_b32_e32 v107, 0
	s_and_saveexec_b64 s[22:23], vcc
	v_lshl_add_u64 v[108:109], v[40:41], 0, s[20:21]
	v_lshl_add_u64 v[110:111], v[38:39], 0, s[20:21]
	v_lshl_add_u64 v[112:113], v[36:37], 0, s[20:21]
	v_lshl_add_u64 v[114:115], v[34:35], 0, s[20:21]
	v_lshl_add_u64 v[116:117], v[32:33], 0, s[20:21]
	v_lshl_add_u64 v[118:119], v[30:31], 0, s[20:21]
	v_lshl_add_u64 v[120:121], v[28:29], 0, s[20:21]
	v_lshl_add_u64 v[122:123], v[26:27], 0, s[20:21]
	global_load_dword v100, v[108:109], off
	global_load_dword v101, v[110:111], off
	global_load_dword v102, v[112:113], off
	global_load_dword v103, v[114:115], off
	global_load_dword v104, v[116:117], off
	global_load_dword v105, v[118:119], off
	global_load_dword v106, v[120:121], off
	global_load_dword v107, v[122:123], off
	s_or_b64 exec, exec, s[22:23]
	s_add_u32 s20, s20, 0x2c200
	s_addc_u32 s21, s21, 0
	s_waitcnt vmcnt(0)
	ds_write_b32 v10, v100
	ds_write_b32 v10, v101 offset:264
	ds_write_b32 v10, v102 offset:528
	ds_write_b32 v10, v103 offset:792
	ds_write_b32 v10, v104 offset:1056
	ds_write_b32 v10, v105 offset:1320
	ds_write_b32 v10, v106 offset:1584
	ds_write_b32 v10, v107 offset:1848
	s_cmp_lg_u32 s20, 0xb0800
	v_add_u32_e32 v10, 0x840, v10
	s_cbranch_scc1 .LBB0_41
	s_branch .LBB0_8


